# v56 + one static s_setprio 1 for waves 0-3 during the attention phase (reset after)
# baseline (speedup 1.0000x reference)
; #define ARGP(i) ka_ptr(ka, (i) * 8)
; template <int MODE, bool FIX> ...
;     const int r32 = lane & 31, hi = lane >> 5;
;     const int b = unit >> 7, rem = unit & 127;
;     int head, qtok, qcol, kcol, vcol, ocol, NTL, lrow0;
;     int s_sub = 0, tl0 = 0;
;     int qrow = 0, qc = 0, kc0 = 0, kr_lo = 0, wa_lo = 0, wa_hi = 0, rs = 0;
;     unsigned colmask = 0u;
;     if (MODE == 0) {
;         const int qblk = rem >> 1, kvh = rem & 1, q0 = qblk * 64;
;         head = kvh * 4 + (wid >> 1); s_sub = wid & 1; qtok = q0 + 32 * s_sub + r32; qcol = head * 64; kcol = 512 + kvh * 64; vcol = 640 + kvh * 64; ocol = head * 64;
;         tl0 = (2 - qblk) > 0 ? (2 - qblk) : 0; const int tl1 = (65 - qblk) < 4 ? (65 - qblk) : 4; NTL = tl1 - tl0 + 1; lrow0 = b * SEQ + q0 - 128 + 64 * tl0;
;     } else {
;         head = rem >> 4; const int r0 = 4 * (rem & 15), rp = wid >> 2, cgp = wid & 3;
;         qrow = r0 + 2 * rp + (r32 >> 4); qc = 16 * cgp + (r32 & 15); qtok = qrow * 64 + qc; qcol = 768 + head * 64; kcol = 1280 + head * 64; vcol = 1792 + head * 64; ocol = 512 + head * 64;
;         kr_lo = (r0 - 4) > 0 ? (r0 - 4) : 0; const int kr_hi = clampi(r0 - 1, 0, 56) + 7; NTL = kr_hi - kr_lo + 1; lrow0 = b * SEQ + kr_lo * 64;
;         kc0 = clampi(16 * cgp - 8, 0, 32); const int cs = clampi(qc - 8, 0, 48);
;         wa_lo = clampi(r0 + 2 * rp - 4, 0, 56); wa_hi = clampi(r0 + 2 * rp - 3, 0, 56) + 7; rs = clampi(qrow - 4, 0, 56);
; #pragma unroll
; __global__ void __launch_bounds__(NWAVES * 64, 2) fwd_kernel(Args args_unused) {
;     ...
;     if (IN(3)) for (int rep = 0; rep < NREP(3); ++rep) {
;         GET_LANE();
;         unsigned char* const ws = ARG_WS();
;         const bf16_t* QKV = (const bf16_t*)(ws + WS_QKV); bf16_t* Ob = (bf16_t*)(ws + WS_O); float* ssq1 = (float*)(ws + (FIRST_OF_2(3) ? WS_DUMMY : WS_SSQ1));
;         const float* sinkp = ARGP(I_SINK); const float* rpbp = ARGP(I_RPB);
;         const int per = (1024 + G - 1) / G;
;         const float MA = ((const float*)(ws + WS_BOUNDS))[0], MB = ((const float*)(ws + WS_BOUNDS))[1];
;         const bool fixA = MA < 48.0f, fixB = MB < 48.0f;
;         for (int i = 0; i < per; ++i) { const int ua = vcu2 * per + i; if (ua < 1024) { if (fixA) att::attn_unit<0, true>(lds, QKV, Ob, ssq1, sinkp, rpbp, ua, tid, lane, wave, MA); else att::attn_unit<0, false>(lds, QKV, Ob, ssq1, sinkp, rpbp, ua, tid, lane, wave, 0.f); } }
.LBB0_568:
	s_cmp_lt_i32 s89, 4
	v_writelane_b32 v255, s94, 2
	s_cselect_b64 s[0:1], -1, 0
	v_writelane_b32 v255, s0, 3
	s_nop 1
	v_writelane_b32 v255, s1, 4
	s_and_b64 s[0:1], s[0:1], s[4:5]
	s_andn2_b64 vcc, exec, s[0:1]
	s_cbranch_vccnz .LBB0_735
	s_abs_i32 s0, s33
	v_cvt_f32_u32_e32 v0, s0
	v_mbcnt_lo_u32_b32 v197, -1, 0
	v_mbcnt_hi_u32_b32 v197, -1, v197
	s_load_dwordx2 s[2:3], s[96:97], 0xb0
	s_waitcnt lgkmcnt(0)
	s_load_dwordx2 s[4:5], s[96:97], 0x50
	s_waitcnt lgkmcnt(0)
	v_rcp_iflag_f32_e32 v0, v0
	v_writelane_b32 v255, s4, 5
	s_load_dwordx2 s[6:7], s[96:97], 0x68
	s_waitcnt lgkmcnt(0)
	s_add_i32 s1, s33, 0x3ff
	v_mul_f32_e32 v0, 0x4f7ffffe, v0
	v_cvt_u32_f32_e32 v0, v0
	v_writelane_b32 v255, s5, 6
	v_writelane_b32 v255, s6, 7
	s_sub_i32 s5, 0, s0
	s_xor_b32 s4, s1, s33
	v_writelane_b32 v255, s7, 8
	v_readfirstlane_b32 s6, v0
	s_mul_i32 s5, s5, s6
	s_mul_hi_u32 s5, s6, s5
	s_abs_i32 s1, s1
	s_add_i32 s6, s6, s5
	s_mul_hi_u32 s5, s1, s6
	s_mul_i32 s6, s5, s0
	s_sub_i32 s1, s1, s6
	s_ashr_i32 s4, s4, 31
	s_add_i32 s6, s5, 1
	s_sub_i32 s7, s1, s0
	s_cmp_ge_u32 s1, s0
	s_cselect_b32 s5, s6, s5
	s_cselect_b32 s1, s7, s1
	s_add_i32 s6, s5, 1
	s_cmp_ge_u32 s1, s0
	s_cselect_b32 s0, s6, s5
	s_xor_b32 s0, s0, s4
	s_sub_i32 s94, s0, s4
	s_cmp_lt_i32 s94, 1
	s_mov_b32 s87, 0
	s_cbranch_scc1 .LBB0_735
	v_mov_b32_e32 v0, 0xc3000
	global_load_dwordx2 v[182:183], v0, s[2:3]
	v_writelane_b32 v255, s56, 0
	v_writelane_b32 v255, s92, 9
	v_add_u32_e32 v188, s71, v197
	v_and_b32_e32 v0, 7, v197
	v_writelane_b32 v255, s93, 10
	v_writelane_b32 v255, s83, 11
	v_writelane_b32 v255, s82, 12
	v_writelane_b32 v255, s90, 13
	v_writelane_b32 v255, s89, 14
	v_writelane_b32 v255, s96, 15
	s_movk_i32 s4, 0x90
	v_lshlrev_b32_e32 v1, 4, v197
	v_writelane_b32 v255, s97, 16
	v_ashrrev_i32_e32 v6, 3, v188
	v_readlane_b32 s0, v255, 2
	s_mul_i32 s0, s85, s0
	s_add_i32 s42, s60, s0
	v_lshlrev_b32_e32 v0, 4, v0
	v_writelane_b32 v255, s85, 1
	s_and_b64 s[0:1], s[18:19], exec
	v_mad_u64_u32 v[178:179], s[0:1], v6, s4, v[0:1]
	v_writelane_b32 v255, s71, 17
	v_ashrrev_i32_e32 v2, 5, v197
	s_cselect_b32 s1, s42, s64
	s_lshr_b32 s85, s95, 7
	s_bfe_u32 s74, s95, 0x10006
	s_cmp_ge_u32 s95, 0x100
	s_cbranch_scc1 .Lp3_prio_done
	s_setprio 1
